# prologue weight-conversion item: all 32 W + 32 gain loads in flight (was one wait per 4-byte load)
# speedup vs baseline: 1.0236x; 1.0236x over previous
; #define LAS __attribute__((address_space(3)))
; DI void conv_item(const float* W, int K, int N, const float* gain, bf16_t* dst, int drow0, float scale, int k0, int n0, LAS float* scr, int lane) {
; #pragma unroll 8
;     for (int i = 0; i < 32; ++i) { const int kk = 2 * i + (lane >> 5); const float g = gain ? gain[k0 + kk] * scale : scale;
;         scr[kk * 33 + (lane & 31)] = W[(size_t)(k0 + kk) * N + n0 + (lane & 31)] * g; }
;     asm volatile("s_waitcnt lgkmcnt(0)" ::: "memory");
.LBB0_81:
	s_lshl_b32 s26, s29, 6
	s_cmp_lg_u64 s[18:19], 0
	s_cselect_b64 s[34:35], -1, 0
	s_ashr_i32 s29, s28, 31
	s_lshl_b64 s[4:5], s[28:29], 2
	s_add_u32 s4, s24, s4
	s_addc_u32 s5, s25, s5
	s_ashr_i32 s27, s26, 31
	v_lshl_add_u64 v[8:9], v[2:3], 0, s[26:27]
	v_lshl_add_u64 v[6:7], s[4:5], 0, v[176:177]
	v_add_u32_e32 v14, s26, v2
	v_lshl_add_u64 v[8:9], v[8:9], 2, s[18:19]
	s_mov_b32 s17, 0
	v_mov_b32_e32 v15, v13
	v_mad_u64_u32 v[16:17], vcc, s30, v14, 0
	s_lshl_b32 s24, s30, 3
	s_mov_b32 s25, 0
	v_lshl_add_u64 v[16:17], v[16:17], 2, v[6:7]
	s_and_b64 vcc, exec, s[34:35]
	s_cbranch_vccz .Lconv_nogain
	global_load_dword v20, v[16:17], off
	v_lshl_add_u64 v[16:17], v[16:17], 0, s[24:25]
	global_load_dword v21, v[16:17], off
	v_lshl_add_u64 v[16:17], v[16:17], 0, s[24:25]
	global_load_dword v22, v[16:17], off
	v_lshl_add_u64 v[16:17], v[16:17], 0, s[24:25]
	global_load_dword v23, v[16:17], off
	v_lshl_add_u64 v[16:17], v[16:17], 0, s[24:25]
	global_load_dword v24, v[16:17], off
	v_lshl_add_u64 v[16:17], v[16:17], 0, s[24:25]
	global_load_dword v25, v[16:17], off
	v_lshl_add_u64 v[16:17], v[16:17], 0, s[24:25]
	global_load_dword v26, v[16:17], off
	v_lshl_add_u64 v[16:17], v[16:17], 0, s[24:25]
	global_load_dword v27, v[16:17], off
	v_lshl_add_u64 v[16:17], v[16:17], 0, s[24:25]
	global_load_dword v28, v[16:17], off
	v_lshl_add_u64 v[16:17], v[16:17], 0, s[24:25]
	global_load_dword v29, v[16:17], off
	v_lshl_add_u64 v[16:17], v[16:17], 0, s[24:25]
	global_load_dword v30, v[16:17], off
	v_lshl_add_u64 v[16:17], v[16:17], 0, s[24:25]
	global_load_dword v31, v[16:17], off
	v_lshl_add_u64 v[16:17], v[16:17], 0, s[24:25]
	global_load_dword v32, v[16:17], off
	v_lshl_add_u64 v[16:17], v[16:17], 0, s[24:25]
	global_load_dword v33, v[16:17], off
	v_lshl_add_u64 v[16:17], v[16:17], 0, s[24:25]
	global_load_dword v34, v[16:17], off
	v_lshl_add_u64 v[16:17], v[16:17], 0, s[24:25]
	global_load_dword v35, v[16:17], off
	v_lshl_add_u64 v[16:17], v[16:17], 0, s[24:25]
	global_load_dword v52, v[8:9], off
	global_load_dword v53, v[8:9], off offset:8
	global_load_dword v54, v[8:9], off offset:16
	global_load_dword v55, v[8:9], off offset:24
	global_load_dword v56, v[8:9], off offset:32
	global_load_dword v57, v[8:9], off offset:40
	global_load_dword v58, v[8:9], off offset:48
	global_load_dword v59, v[8:9], off offset:56
	global_load_dword v60, v[8:9], off offset:64
	global_load_dword v61, v[8:9], off offset:72
	global_load_dword v62, v[8:9], off offset:80
	global_load_dword v63, v[8:9], off offset:88
	global_load_dword v64, v[8:9], off offset:96
	global_load_dword v65, v[8:9], off offset:104
	global_load_dword v66, v[8:9], off offset:112
	global_load_dword v67, v[8:9], off offset:120
	global_load_dword v36, v[16:17], off
	v_lshl_add_u64 v[16:17], v[16:17], 0, s[24:25]
	global_load_dword v37, v[16:17], off
	v_lshl_add_u64 v[16:17], v[16:17], 0, s[24:25]
	global_load_dword v38, v[16:17], off
	v_lshl_add_u64 v[16:17], v[16:17], 0, s[24:25]
	global_load_dword v39, v[16:17], off
	v_lshl_add_u64 v[16:17], v[16:17], 0, s[24:25]
	global_load_dword v40, v[16:17], off
	v_lshl_add_u64 v[16:17], v[16:17], 0, s[24:25]
	global_load_dword v41, v[16:17], off
	v_lshl_add_u64 v[16:17], v[16:17], 0, s[24:25]
	global_load_dword v42, v[16:17], off
	v_lshl_add_u64 v[16:17], v[16:17], 0, s[24:25]
	global_load_dword v43, v[16:17], off
	v_lshl_add_u64 v[16:17], v[16:17], 0, s[24:25]
	global_load_dword v44, v[16:17], off
	v_lshl_add_u64 v[16:17], v[16:17], 0, s[24:25]
	global_load_dword v45, v[16:17], off
	v_lshl_add_u64 v[16:17], v[16:17], 0, s[24:25]
	global_load_dword v46, v[16:17], off
	v_lshl_add_u64 v[16:17], v[16:17], 0, s[24:25]
	global_load_dword v47, v[16:17], off
	v_lshl_add_u64 v[16:17], v[16:17], 0, s[24:25]
	global_load_dword v48, v[16:17], off
	v_lshl_add_u64 v[16:17], v[16:17], 0, s[24:25]
	global_load_dword v49, v[16:17], off
	v_lshl_add_u64 v[16:17], v[16:17], 0, s[24:25]
	global_load_dword v50, v[16:17], off
	v_lshl_add_u64 v[16:17], v[16:17], 0, s[24:25]
	global_load_dword v51, v[16:17], off
	s_waitcnt vmcnt(16)
	global_load_dword v68, v[8:9], off offset:128
	global_load_dword v69, v[8:9], off offset:136
	global_load_dword v70, v[8:9], off offset:144
	global_load_dword v71, v[8:9], off offset:152
	global_load_dword v72, v[8:9], off offset:160
	global_load_dword v73, v[8:9], off offset:168
	global_load_dword v74, v[8:9], off offset:176
	global_load_dword v75, v[8:9], off offset:184
	global_load_dword v76, v[8:9], off offset:192
	global_load_dword v77, v[8:9], off offset:200
	global_load_dword v78, v[8:9], off offset:208
	global_load_dword v79, v[8:9], off offset:216
	global_load_dword v80, v[8:9], off offset:224
	global_load_dword v81, v[8:9], off offset:232
	global_load_dword v82, v[8:9], off offset:240
	global_load_dword v83, v[8:9], off offset:248
	v_mul_f32_e32 v52, v5, v52
	v_mul_f32_e32 v20, v52, v20
	ds_write_b32 v13, v20
	v_mul_f32_e32 v53, v5, v53
	v_mul_f32_e32 v21, v53, v21
	ds_write_b32 v13, v21 offset:264
	v_mul_f32_e32 v54, v5, v54
	v_mul_f32_e32 v22, v54, v22
	ds_write_b32 v13, v22 offset:528
	v_mul_f32_e32 v55, v5, v55
	v_mul_f32_e32 v23, v55, v23
	ds_write_b32 v13, v23 offset:792
	v_mul_f32_e32 v56, v5, v56
	v_mul_f32_e32 v24, v56, v24
	ds_write_b32 v13, v24 offset:1056
	v_mul_f32_e32 v57, v5, v57
	v_mul_f32_e32 v25, v57, v25
	ds_write_b32 v13, v25 offset:1320
	v_mul_f32_e32 v58, v5, v58
	v_mul_f32_e32 v26, v58, v26
	ds_write_b32 v13, v26 offset:1584
	v_mul_f32_e32 v59, v5, v59
	v_mul_f32_e32 v27, v59, v27
	ds_write_b32 v13, v27 offset:1848
	v_mul_f32_e32 v60, v5, v60
	v_mul_f32_e32 v28, v60, v28
	ds_write_b32 v13, v28 offset:2112
	v_mul_f32_e32 v61, v5, v61
	v_mul_f32_e32 v29, v61, v29
	ds_write_b32 v13, v29 offset:2376
	v_mul_f32_e32 v62, v5, v62
	v_mul_f32_e32 v30, v62, v30
	ds_write_b32 v13, v30 offset:2640
	v_mul_f32_e32 v63, v5, v63
	v_mul_f32_e32 v31, v63, v31
	ds_write_b32 v13, v31 offset:2904
	v_mul_f32_e32 v64, v5, v64
	v_mul_f32_e32 v32, v64, v32
	ds_write_b32 v13, v32 offset:3168
	v_mul_f32_e32 v65, v5, v65
	v_mul_f32_e32 v33, v65, v33
	ds_write_b32 v13, v33 offset:3432
	v_mul_f32_e32 v66, v5, v66
	v_mul_f32_e32 v34, v66, v34
	ds_write_b32 v13, v34 offset:3696
	v_mul_f32_e32 v67, v5, v67
	v_mul_f32_e32 v35, v67, v35
	ds_write_b32 v13, v35 offset:3960
	s_waitcnt vmcnt(0)
; #define LAS __attribute__((address_space(3)))
; DI void conv_item(const float* W, int K, int N, const float* gain, bf16_t* dst, int drow0, float scale, int k0, int n0, LAS float* scr, int lane) {
; #pragma unroll 8
;     for (int i = 0; i < 32; ++i) { const int kk = 2 * i + (lane >> 5); const float g = gain ? gain[k0 + kk] * scale : scale;
;         scr[kk * 33 + (lane & 31)] = W[(size_t)(k0 + kk) * N + n0 + (lane & 31)] * g; }
;     asm volatile("s_waitcnt lgkmcnt(0)" ::: "memory");
	v_mul_f32_e32 v68, v5, v68
	v_mul_f32_e32 v36, v68, v36
	ds_write_b32 v13, v36 offset:4224
	v_mul_f32_e32 v69, v5, v69
	v_mul_f32_e32 v37, v69, v37
	ds_write_b32 v13, v37 offset:4488
	v_mul_f32_e32 v70, v5, v70
	v_mul_f32_e32 v38, v70, v38
	ds_write_b32 v13, v38 offset:4752
	v_mul_f32_e32 v71, v5, v71
	v_mul_f32_e32 v39, v71, v39
	ds_write_b32 v13, v39 offset:5016
	v_mul_f32_e32 v72, v5, v72
	v_mul_f32_e32 v40, v72, v40
	ds_write_b32 v13, v40 offset:5280
	v_mul_f32_e32 v73, v5, v73
	v_mul_f32_e32 v41, v73, v41
	ds_write_b32 v13, v41 offset:5544
	v_mul_f32_e32 v74, v5, v74
	v_mul_f32_e32 v42, v74, v42
	ds_write_b32 v13, v42 offset:5808
	v_mul_f32_e32 v75, v5, v75
	v_mul_f32_e32 v43, v75, v43
	ds_write_b32 v13, v43 offset:6072
	v_mul_f32_e32 v76, v5, v76
	v_mul_f32_e32 v44, v76, v44
	ds_write_b32 v13, v44 offset:6336
	v_mul_f32_e32 v77, v5, v77
	v_mul_f32_e32 v45, v77, v45
	ds_write_b32 v13, v45 offset:6600
	v_mul_f32_e32 v78, v5, v78
	v_mul_f32_e32 v46, v78, v46
	ds_write_b32 v13, v46 offset:6864
	v_mul_f32_e32 v79, v5, v79
	v_mul_f32_e32 v47, v79, v47
	ds_write_b32 v13, v47 offset:7128
	v_mul_f32_e32 v80, v5, v80
	v_mul_f32_e32 v48, v80, v48
	ds_write_b32 v13, v48 offset:7392
	v_mul_f32_e32 v81, v5, v81
	v_mul_f32_e32 v49, v81, v49
	ds_write_b32 v13, v49 offset:7656
	v_mul_f32_e32 v82, v5, v82
	v_mul_f32_e32 v50, v82, v50
	ds_write_b32 v13, v50 offset:7920
	v_mul_f32_e32 v83, v5, v83
	v_mul_f32_e32 v51, v83, v51
	ds_write_b32 v13, v51 offset:8184
	s_branch .LBB0_26
.Lconv_nogain:
	global_load_dword v20, v[16:17], off
	v_lshl_add_u64 v[16:17], v[16:17], 0, s[24:25]
	global_load_dword v21, v[16:17], off
	v_lshl_add_u64 v[16:17], v[16:17], 0, s[24:25]
	global_load_dword v22, v[16:17], off
	v_lshl_add_u64 v[16:17], v[16:17], 0, s[24:25]
	global_load_dword v23, v[16:17], off
	v_lshl_add_u64 v[16:17], v[16:17], 0, s[24:25]
	global_load_dword v24, v[16:17], off
	v_lshl_add_u64 v[16:17], v[16:17], 0, s[24:25]
	global_load_dword v25, v[16:17], off
	v_lshl_add_u64 v[16:17], v[16:17], 0, s[24:25]
	global_load_dword v26, v[16:17], off
	v_lshl_add_u64 v[16:17], v[16:17], 0, s[24:25]
	global_load_dword v27, v[16:17], off
	v_lshl_add_u64 v[16:17], v[16:17], 0, s[24:25]
	global_load_dword v28, v[16:17], off
	v_lshl_add_u64 v[16:17], v[16:17], 0, s[24:25]
	global_load_dword v29, v[16:17], off
	v_lshl_add_u64 v[16:17], v[16:17], 0, s[24:25]
	global_load_dword v30, v[16:17], off
	v_lshl_add_u64 v[16:17], v[16:17], 0, s[24:25]
	global_load_dword v31, v[16:17], off
	v_lshl_add_u64 v[16:17], v[16:17], 0, s[24:25]
	global_load_dword v32, v[16:17], off
	v_lshl_add_u64 v[16:17], v[16:17], 0, s[24:25]
	global_load_dword v33, v[16:17], off
	v_lshl_add_u64 v[16:17], v[16:17], 0, s[24:25]
	global_load_dword v34, v[16:17], off
	v_lshl_add_u64 v[16:17], v[16:17], 0, s[24:25]
	global_load_dword v35, v[16:17], off
	v_lshl_add_u64 v[16:17], v[16:17], 0, s[24:25]
	global_load_dword v36, v[16:17], off
	v_lshl_add_u64 v[16:17], v[16:17], 0, s[24:25]
	global_load_dword v37, v[16:17], off
	v_lshl_add_u64 v[16:17], v[16:17], 0, s[24:25]
	global_load_dword v38, v[16:17], off
	v_lshl_add_u64 v[16:17], v[16:17], 0, s[24:25]
	global_load_dword v39, v[16:17], off
	v_lshl_add_u64 v[16:17], v[16:17], 0, s[24:25]
	global_load_dword v40, v[16:17], off
	v_lshl_add_u64 v[16:17], v[16:17], 0, s[24:25]
	global_load_dword v41, v[16:17], off
	v_lshl_add_u64 v[16:17], v[16:17], 0, s[24:25]
	global_load_dword v42, v[16:17], off
	v_lshl_add_u64 v[16:17], v[16:17], 0, s[24:25]
	global_load_dword v43, v[16:17], off
	v_lshl_add_u64 v[16:17], v[16:17], 0, s[24:25]
	global_load_dword v44, v[16:17], off
	v_lshl_add_u64 v[16:17], v[16:17], 0, s[24:25]
	global_load_dword v45, v[16:17], off
	v_lshl_add_u64 v[16:17], v[16:17], 0, s[24:25]
	global_load_dword v46, v[16:17], off
	v_lshl_add_u64 v[16:17], v[16:17], 0, s[24:25]
	global_load_dword v47, v[16:17], off
	v_lshl_add_u64 v[16:17], v[16:17], 0, s[24:25]
	global_load_dword v48, v[16:17], off
	v_lshl_add_u64 v[16:17], v[16:17], 0, s[24:25]
	global_load_dword v49, v[16:17], off
	v_lshl_add_u64 v[16:17], v[16:17], 0, s[24:25]
	global_load_dword v50, v[16:17], off
	v_lshl_add_u64 v[16:17], v[16:17], 0, s[24:25]
	global_load_dword v51, v[16:17], off
	s_waitcnt vmcnt(0)
	v_mul_f32_e32 v20, v5, v20
	ds_write_b32 v13, v20
	v_mul_f32_e32 v21, v5, v21
	ds_write_b32 v13, v21 offset:264
	v_mul_f32_e32 v22, v5, v22
	ds_write_b32 v13, v22 offset:528
	v_mul_f32_e32 v23, v5, v23
	ds_write_b32 v13, v23 offset:792
	v_mul_f32_e32 v24, v5, v24
	ds_write_b32 v13, v24 offset:1056
	v_mul_f32_e32 v25, v5, v25
	ds_write_b32 v13, v25 offset:1320
	v_mul_f32_e32 v26, v5, v26
	ds_write_b32 v13, v26 offset:1584
	v_mul_f32_e32 v27, v5, v27
	ds_write_b32 v13, v27 offset:1848
	v_mul_f32_e32 v28, v5, v28
	ds_write_b32 v13, v28 offset:2112
	v_mul_f32_e32 v29, v5, v29
	ds_write_b32 v13, v29 offset:2376
	v_mul_f32_e32 v30, v5, v30
	ds_write_b32 v13, v30 offset:2640
	v_mul_f32_e32 v31, v5, v31
	ds_write_b32 v13, v31 offset:2904
	v_mul_f32_e32 v32, v5, v32
	ds_write_b32 v13, v32 offset:3168
	v_mul_f32_e32 v33, v5, v33
	ds_write_b32 v13, v33 offset:3432
	v_mul_f32_e32 v34, v5, v34
	ds_write_b32 v13, v34 offset:3696
	v_mul_f32_e32 v35, v5, v35
	ds_write_b32 v13, v35 offset:3960
	v_mul_f32_e32 v36, v5, v36
	ds_write_b32 v13, v36 offset:4224
	v_mul_f32_e32 v37, v5, v37
	ds_write_b32 v13, v37 offset:4488
	v_mul_f32_e32 v38, v5, v38
	ds_write_b32 v13, v38 offset:4752
	v_mul_f32_e32 v39, v5, v39
	ds_write_b32 v13, v39 offset:5016
	v_mul_f32_e32 v40, v5, v40
	ds_write_b32 v13, v40 offset:5280
	v_mul_f32_e32 v41, v5, v41
	ds_write_b32 v13, v41 offset:5544
	v_mul_f32_e32 v42, v5, v42
	ds_write_b32 v13, v42 offset:5808
	v_mul_f32_e32 v43, v5, v43
	ds_write_b32 v13, v43 offset:6072
	v_mul_f32_e32 v44, v5, v44
	ds_write_b32 v13, v44 offset:6336
	v_mul_f32_e32 v45, v5, v45
	ds_write_b32 v13, v45 offset:6600
	v_mul_f32_e32 v46, v5, v46
	ds_write_b32 v13, v46 offset:6864
	v_mul_f32_e32 v47, v5, v47
	ds_write_b32 v13, v47 offset:7128
	v_mul_f32_e32 v48, v5, v48
	ds_write_b32 v13, v48 offset:7392
	v_mul_f32_e32 v49, v5, v49
	ds_write_b32 v13, v49 offset:7656
	v_mul_f32_e32 v50, v5, v50
	ds_write_b32 v13, v50 offset:7920
	v_mul_f32_e32 v51, v5, v51
	ds_write_b32 v13, v51 offset:8184
	s_branch .LBB0_26
